# v085 + RG-LRU conv section regenerated: thread owns one channel group for rows t/24+21j so f32 tap weights and bias are read from LDS once per tile instead of per item (LDS reads 42 -> 22 per thread)
# speedup vs baseline: 1.0435x; 1.0118x over previous
; #define LAS __attribute__((address_space(3)))
; DI u32x4 pack8f(const float (&f)[8]) { u32x4 r; r[0] = pk2(f[0], f[1]); r[1] = pk2(f[2], f[3]); r[2] = pk2(f[4], f[5]); r[3] = pk2(f[6], f[7]); return r; }
; DI void phase_rglru(const Params& p, unsigned char* shm) {
;     ...
; #pragma unroll
;             for (int j = 0; j < 3; ++j) {
;                 const int q = tid + 512 * j, cc = q % 24;
;                 float a8[8];
;                 { const f32x4 b0 = *(const LAS f32x4*)(cw + 768 + 8 * cc), b1 = *(const LAS f32x4*)(cw + 768 + 8 * cc + 4);
; #pragma unroll
;                   for (int e = 0; e < 4; ++e) { a8[e] = b0[e]; a8[4 + e] = b1[e]; } }
; #pragma unroll
;                 for (int jj = 0; jj < 4; ++jj) {
;                     float xin[8]; { const u32x4 xraw = *(const LAS u32x4*)(lds + XR + jj * TR + loff[j]); unpack8(xraw, xin); }
;                     const f32x4 w0 = *(const LAS f32x4*)(cw + jj * 192 + 8 * cc), w1 = *(const LAS f32x4*)(cw + jj * 192 + 8 * cc + 4);
; #pragma unroll
;                     for (int e = 0; e < 4; ++e) { a8[e] += w0[e] * xin[e]; a8[4 + e] += w1[e] * xin[4 + e]; }
;                 }
;                 *(LAS u32x4*)(lds + XC + loff[j]) = pack8f(a8);
;             }
.LBB0_845:
	s_waitcnt lgkmcnt(0)
	s_barrier
	v_mul_u32_u24_e32 v205, 0xaab, v192
	v_lshrrev_b32_e32 v205, 16, v205
	v_mul_u32_u24_e32 v170, 24, v205
	v_sub_u32_e32 v170, v192, v170
	v_mul_u32_u24_e32 v205, 0x190, v205
	v_lshl_add_u32 v205, v170, 4, v205
	v_lshlrev_b32_e32 v170, 5, v170
	v_add_u32_e32 v170, 0x1f900, v170
	ds_read_b128 v[144:147], v170 offset:3072
	ds_read_b128 v[148:151], v170 offset:3088
	ds_read_b128 v[210:213], v170
	ds_read_b128 v[214:217], v170 offset:16
	ds_read_b128 v[218:221], v170 offset:768
	ds_read_b128 v[222:225], v170 offset:784
	ds_read_b128 v[226:229], v170 offset:1536
	ds_read_b128 v[230:233], v170 offset:1552
	ds_read_b128 v[234:237], v170 offset:2304
	ds_read_b128 v[238:241], v170 offset:2320
	ds_read_b128 v[128:131], v205
	ds_read_b128 v[132:135], v205 offset:400
	ds_read_b128 v[136:139], v205 offset:800
	ds_read_b128 v[140:143], v205 offset:1200
	s_waitcnt lgkmcnt(3)
	v_lshlrev_b32_e32 v170, 16, v128
	v_and_b32_e32 v171, 0xffff0000, v128
	v_pk_fma_f32 v[120:121], v[210:211], v[170:171], v[144:145]
	v_lshlrev_b32_e32 v170, 16, v129
	v_and_b32_e32 v171, 0xffff0000, v129
	v_pk_fma_f32 v[122:123], v[212:213], v[170:171], v[146:147]
	v_lshlrev_b32_e32 v170, 16, v130
	v_and_b32_e32 v171, 0xffff0000, v130
	v_pk_fma_f32 v[124:125], v[214:215], v[170:171], v[148:149]
	v_lshlrev_b32_e32 v170, 16, v131
	v_and_b32_e32 v171, 0xffff0000, v131
	v_pk_fma_f32 v[126:127], v[216:217], v[170:171], v[150:151]
	s_waitcnt lgkmcnt(2)
	v_lshlrev_b32_e32 v170, 16, v132
	v_and_b32_e32 v171, 0xffff0000, v132
	v_pk_fma_f32 v[120:121], v[218:219], v[170:171], v[120:121]
	v_lshlrev_b32_e32 v170, 16, v133
	v_and_b32_e32 v171, 0xffff0000, v133
	v_pk_fma_f32 v[122:123], v[220:221], v[170:171], v[122:123]
	v_lshlrev_b32_e32 v170, 16, v134
	v_and_b32_e32 v171, 0xffff0000, v134
	v_pk_fma_f32 v[124:125], v[222:223], v[170:171], v[124:125]
	v_lshlrev_b32_e32 v170, 16, v135
	v_and_b32_e32 v171, 0xffff0000, v135
	v_pk_fma_f32 v[126:127], v[224:225], v[170:171], v[126:127]
	s_waitcnt lgkmcnt(1)
	v_lshlrev_b32_e32 v170, 16, v136
	v_and_b32_e32 v171, 0xffff0000, v136
	v_pk_fma_f32 v[120:121], v[226:227], v[170:171], v[120:121]
	v_lshlrev_b32_e32 v170, 16, v137
	v_and_b32_e32 v171, 0xffff0000, v137
	v_pk_fma_f32 v[122:123], v[228:229], v[170:171], v[122:123]
	v_lshlrev_b32_e32 v170, 16, v138
	v_and_b32_e32 v171, 0xffff0000, v138
	v_pk_fma_f32 v[124:125], v[230:231], v[170:171], v[124:125]
	v_lshlrev_b32_e32 v170, 16, v139
	v_and_b32_e32 v171, 0xffff0000, v139
	v_pk_fma_f32 v[126:127], v[232:233], v[170:171], v[126:127]
	s_waitcnt lgkmcnt(0)
	v_lshlrev_b32_e32 v170, 16, v140
	v_and_b32_e32 v171, 0xffff0000, v140
	v_pk_fma_f32 v[120:121], v[234:235], v[170:171], v[120:121]
	v_lshlrev_b32_e32 v170, 16, v141
	v_and_b32_e32 v171, 0xffff0000, v141
	v_pk_fma_f32 v[122:123], v[236:237], v[170:171], v[122:123]
	v_lshlrev_b32_e32 v170, 16, v142
	v_and_b32_e32 v171, 0xffff0000, v142
	v_pk_fma_f32 v[124:125], v[238:239], v[170:171], v[124:125]
	v_lshlrev_b32_e32 v170, 16, v143
	v_and_b32_e32 v171, 0xffff0000, v143
	v_pk_fma_f32 v[126:127], v[240:241], v[170:171], v[126:127]
	ds_read_b128 v[128:131], v205 offset:8400
	ds_read_b128 v[132:135], v205 offset:8800
	ds_read_b128 v[136:139], v205 offset:9200
	ds_read_b128 v[140:143], v205 offset:9600
	v_cvt_pk_bf16_f32 v120, v120, v121
	v_cvt_pk_bf16_f32 v121, v122, v123
	v_cvt_pk_bf16_f32 v122, v124, v125
	v_cvt_pk_bf16_f32 v123, v126, v127
	ds_write_b128 v205, v[120:123] offset:26880
	s_waitcnt lgkmcnt(4)
	v_lshlrev_b32_e32 v170, 16, v128
	v_and_b32_e32 v171, 0xffff0000, v128
	v_pk_fma_f32 v[120:121], v[210:211], v[170:171], v[144:145]
	v_lshlrev_b32_e32 v170, 16, v129
	v_and_b32_e32 v171, 0xffff0000, v129
	v_pk_fma_f32 v[122:123], v[212:213], v[170:171], v[146:147]
	v_lshlrev_b32_e32 v170, 16, v130
	v_and_b32_e32 v171, 0xffff0000, v130
	v_pk_fma_f32 v[124:125], v[214:215], v[170:171], v[148:149]
	v_lshlrev_b32_e32 v170, 16, v131
	v_and_b32_e32 v171, 0xffff0000, v131
	v_pk_fma_f32 v[126:127], v[216:217], v[170:171], v[150:151]
	s_waitcnt lgkmcnt(3)
	v_lshlrev_b32_e32 v170, 16, v132
	v_and_b32_e32 v171, 0xffff0000, v132
	v_pk_fma_f32 v[120:121], v[218:219], v[170:171], v[120:121]
	v_lshlrev_b32_e32 v170, 16, v133
	v_and_b32_e32 v171, 0xffff0000, v133
	v_pk_fma_f32 v[122:123], v[220:221], v[170:171], v[122:123]
	v_lshlrev_b32_e32 v170, 16, v134
	v_and_b32_e32 v171, 0xffff0000, v134
	v_pk_fma_f32 v[124:125], v[222:223], v[170:171], v[124:125]
	v_lshlrev_b32_e32 v170, 16, v135
	v_and_b32_e32 v171, 0xffff0000, v135
	v_pk_fma_f32 v[126:127], v[224:225], v[170:171], v[126:127]
	s_waitcnt lgkmcnt(2)
	v_lshlrev_b32_e32 v170, 16, v136
	v_and_b32_e32 v171, 0xffff0000, v136
	v_pk_fma_f32 v[120:121], v[226:227], v[170:171], v[120:121]
	v_lshlrev_b32_e32 v170, 16, v137
	v_and_b32_e32 v171, 0xffff0000, v137
	v_pk_fma_f32 v[122:123], v[228:229], v[170:171], v[122:123]
	v_lshlrev_b32_e32 v170, 16, v138
	v_and_b32_e32 v171, 0xffff0000, v138
	v_pk_fma_f32 v[124:125], v[230:231], v[170:171], v[124:125]
	v_lshlrev_b32_e32 v170, 16, v139
	v_and_b32_e32 v171, 0xffff0000, v139
	v_pk_fma_f32 v[126:127], v[232:233], v[170:171], v[126:127]
	s_waitcnt lgkmcnt(1)
	v_lshlrev_b32_e32 v170, 16, v140
	v_and_b32_e32 v171, 0xffff0000, v140
	v_pk_fma_f32 v[120:121], v[234:235], v[170:171], v[120:121]
	v_lshlrev_b32_e32 v170, 16, v141
	v_and_b32_e32 v171, 0xffff0000, v141
	v_pk_fma_f32 v[122:123], v[236:237], v[170:171], v[122:123]
	v_lshlrev_b32_e32 v170, 16, v142
	v_and_b32_e32 v171, 0xffff0000, v142
	v_pk_fma_f32 v[124:125], v[238:239], v[170:171], v[124:125]
	v_lshlrev_b32_e32 v170, 16, v143
	v_and_b32_e32 v171, 0xffff0000, v143
	v_pk_fma_f32 v[126:127], v[240:241], v[170:171], v[126:127]
	ds_read_b128 v[128:131], v205 offset:16800
	ds_read_b128 v[132:135], v205 offset:17200
	ds_read_b128 v[136:139], v205 offset:17600
	ds_read_b128 v[140:143], v205 offset:18000
	v_cvt_pk_bf16_f32 v120, v120, v121
	v_cvt_pk_bf16_f32 v121, v122, v123
	v_cvt_pk_bf16_f32 v122, v124, v125
	v_cvt_pk_bf16_f32 v123, v126, v127
	ds_write_b128 v205, v[120:123] offset:35280
	s_waitcnt lgkmcnt(4)
; #define LAS __attribute__((address_space(3)))
; DI u32x4 pack8f(const float (&f)[8]) { u32x4 r; r[0] = pk2(f[0], f[1]); r[1] = pk2(f[2], f[3]); r[2] = pk2(f[4], f[5]); r[3] = pk2(f[6], f[7]); return r; }
; DI void phase_rglru(const Params& p, unsigned char* shm) {
;     ...
; #pragma unroll
;             for (int j = 0; j < 3; ++j) {
;                 const int q = tid + 512 * j, cc = q % 24;
;                 float a8[8];
;                 { const f32x4 b0 = *(const LAS f32x4*)(cw + 768 + 8 * cc), b1 = *(const LAS f32x4*)(cw + 768 + 8 * cc + 4);
; #pragma unroll
;                   for (int e = 0; e < 4; ++e) { a8[e] = b0[e]; a8[4 + e] = b1[e]; } }
; #pragma unroll
;                 for (int jj = 0; jj < 4; ++jj) {
;                     float xin[8]; { const u32x4 xraw = *(const LAS u32x4*)(lds + XR + jj * TR + loff[j]); unpack8(xraw, xin); }
;                     const f32x4 w0 = *(const LAS f32x4*)(cw + jj * 192 + 8 * cc), w1 = *(const LAS f32x4*)(cw + jj * 192 + 8 * cc + 4);
; #pragma unroll
;                     for (int e = 0; e < 4; ++e) { a8[e] += w0[e] * xin[e]; a8[4 + e] += w1[e] * xin[4 + e]; }
;                 }
;                 *(LAS u32x4*)(lds + XC + loff[j]) = pack8f(a8);
;             }
	v_lshlrev_b32_e32 v170, 16, v128
	v_and_b32_e32 v171, 0xffff0000, v128
	v_pk_fma_f32 v[120:121], v[210:211], v[170:171], v[144:145]
	v_lshlrev_b32_e32 v170, 16, v129
	v_and_b32_e32 v171, 0xffff0000, v129
	v_pk_fma_f32 v[122:123], v[212:213], v[170:171], v[146:147]
	v_lshlrev_b32_e32 v170, 16, v130
	v_and_b32_e32 v171, 0xffff0000, v130
	v_pk_fma_f32 v[124:125], v[214:215], v[170:171], v[148:149]
	v_lshlrev_b32_e32 v170, 16, v131
	v_and_b32_e32 v171, 0xffff0000, v131
	v_pk_fma_f32 v[126:127], v[216:217], v[170:171], v[150:151]
	s_waitcnt lgkmcnt(3)
	v_lshlrev_b32_e32 v170, 16, v132
	v_and_b32_e32 v171, 0xffff0000, v132
	v_pk_fma_f32 v[120:121], v[218:219], v[170:171], v[120:121]
	v_lshlrev_b32_e32 v170, 16, v133
	v_and_b32_e32 v171, 0xffff0000, v133
	v_pk_fma_f32 v[122:123], v[220:221], v[170:171], v[122:123]
	v_lshlrev_b32_e32 v170, 16, v134
	v_and_b32_e32 v171, 0xffff0000, v134
	v_pk_fma_f32 v[124:125], v[222:223], v[170:171], v[124:125]
	v_lshlrev_b32_e32 v170, 16, v135
	v_and_b32_e32 v171, 0xffff0000, v135
	v_pk_fma_f32 v[126:127], v[224:225], v[170:171], v[126:127]
	s_waitcnt lgkmcnt(2)
	v_lshlrev_b32_e32 v170, 16, v136
	v_and_b32_e32 v171, 0xffff0000, v136
	v_pk_fma_f32 v[120:121], v[226:227], v[170:171], v[120:121]
	v_lshlrev_b32_e32 v170, 16, v137
	v_and_b32_e32 v171, 0xffff0000, v137
	v_pk_fma_f32 v[122:123], v[228:229], v[170:171], v[122:123]
	v_lshlrev_b32_e32 v170, 16, v138
	v_and_b32_e32 v171, 0xffff0000, v138
	v_pk_fma_f32 v[124:125], v[230:231], v[170:171], v[124:125]
	v_lshlrev_b32_e32 v170, 16, v139
	v_and_b32_e32 v171, 0xffff0000, v139
	v_pk_fma_f32 v[126:127], v[232:233], v[170:171], v[126:127]
	s_waitcnt lgkmcnt(1)
	v_lshlrev_b32_e32 v170, 16, v140
	v_and_b32_e32 v171, 0xffff0000, v140
	v_pk_fma_f32 v[120:121], v[234:235], v[170:171], v[120:121]
	v_lshlrev_b32_e32 v170, 16, v141
	v_and_b32_e32 v171, 0xffff0000, v141
	v_pk_fma_f32 v[122:123], v[236:237], v[170:171], v[122:123]
	v_lshlrev_b32_e32 v170, 16, v142
	v_and_b32_e32 v171, 0xffff0000, v142
	v_pk_fma_f32 v[124:125], v[238:239], v[170:171], v[124:125]
	v_lshlrev_b32_e32 v170, 16, v143
	v_and_b32_e32 v171, 0xffff0000, v143
	v_pk_fma_f32 v[126:127], v[240:241], v[170:171], v[126:127]
	v_cvt_pk_bf16_f32 v120, v120, v121
	v_cvt_pk_bf16_f32 v121, v122, v123
	v_cvt_pk_bf16_f32 v122, v124, v125
	v_cvt_pk_bf16_f32 v123, v126, v127
	ds_write_b128 v205, v[120:123] offset:43680
	v_cmp_gt_u32_e32 vcc, 24, v192
	s_and_saveexec_b64 s[2:3], vcc
	s_cbranch_execz .Lconv_x_done
	ds_read_b128 v[128:131], v205 offset:25200
	ds_read_b128 v[132:135], v205 offset:25600
	ds_read_b128 v[136:139], v205 offset:26000
	ds_read_b128 v[140:143], v205 offset:26400
	s_waitcnt lgkmcnt(3)
	v_lshlrev_b32_e32 v170, 16, v128
	v_and_b32_e32 v171, 0xffff0000, v128
	v_pk_fma_f32 v[120:121], v[210:211], v[170:171], v[144:145]
	v_lshlrev_b32_e32 v170, 16, v129
	v_and_b32_e32 v171, 0xffff0000, v129
	v_pk_fma_f32 v[122:123], v[212:213], v[170:171], v[146:147]
	v_lshlrev_b32_e32 v170, 16, v130
	v_and_b32_e32 v171, 0xffff0000, v130
	v_pk_fma_f32 v[124:125], v[214:215], v[170:171], v[148:149]
	v_lshlrev_b32_e32 v170, 16, v131
	v_and_b32_e32 v171, 0xffff0000, v131
	v_pk_fma_f32 v[126:127], v[216:217], v[170:171], v[150:151]
	s_waitcnt lgkmcnt(2)
	v_lshlrev_b32_e32 v170, 16, v132
	v_and_b32_e32 v171, 0xffff0000, v132
	v_pk_fma_f32 v[120:121], v[218:219], v[170:171], v[120:121]
	v_lshlrev_b32_e32 v170, 16, v133
	v_and_b32_e32 v171, 0xffff0000, v133
	v_pk_fma_f32 v[122:123], v[220:221], v[170:171], v[122:123]
	v_lshlrev_b32_e32 v170, 16, v134
	v_and_b32_e32 v171, 0xffff0000, v134
	v_pk_fma_f32 v[124:125], v[222:223], v[170:171], v[124:125]
	v_lshlrev_b32_e32 v170, 16, v135
	v_and_b32_e32 v171, 0xffff0000, v135
	v_pk_fma_f32 v[126:127], v[224:225], v[170:171], v[126:127]
	s_waitcnt lgkmcnt(1)
	v_lshlrev_b32_e32 v170, 16, v136
	v_and_b32_e32 v171, 0xffff0000, v136
	v_pk_fma_f32 v[120:121], v[226:227], v[170:171], v[120:121]
	v_lshlrev_b32_e32 v170, 16, v137
	v_and_b32_e32 v171, 0xffff0000, v137
	v_pk_fma_f32 v[122:123], v[228:229], v[170:171], v[122:123]
	v_lshlrev_b32_e32 v170, 16, v138
	v_and_b32_e32 v171, 0xffff0000, v138
	v_pk_fma_f32 v[124:125], v[230:231], v[170:171], v[124:125]
	v_lshlrev_b32_e32 v170, 16, v139
	v_and_b32_e32 v171, 0xffff0000, v139
	v_pk_fma_f32 v[126:127], v[232:233], v[170:171], v[126:127]
	s_waitcnt lgkmcnt(0)
	v_lshlrev_b32_e32 v170, 16, v140
	v_and_b32_e32 v171, 0xffff0000, v140
	v_pk_fma_f32 v[120:121], v[234:235], v[170:171], v[120:121]
	v_lshlrev_b32_e32 v170, 16, v141
	v_and_b32_e32 v171, 0xffff0000, v141
	v_pk_fma_f32 v[122:123], v[236:237], v[170:171], v[122:123]
	v_lshlrev_b32_e32 v170, 16, v142
	v_and_b32_e32 v171, 0xffff0000, v142
	v_pk_fma_f32 v[124:125], v[238:239], v[170:171], v[124:125]
	v_lshlrev_b32_e32 v170, 16, v143
	v_and_b32_e32 v171, 0xffff0000, v143
	v_pk_fma_f32 v[126:127], v[240:241], v[170:171], v[126:127]
	v_cvt_pk_bf16_f32 v120, v120, v121
	v_cvt_pk_bf16_f32 v121, v122, v123
	v_cvt_pk_bf16_f32 v122, v124, v125
	v_cvt_pk_bf16_f32 v123, v126, v127
	ds_write_b128 v205, v[120:123] offset:52080
; #define LAS __attribute__((address_space(3)))
; DI void phase_rglru(const Params& p, unsigned char* shm) {
;     ...
;             __syncthreads();
;             {
; #pragma unroll
;                 for (int u = 0; u < 2; ++u) {
;                     if (u == 1 && w >= 4) break;
;                     f32x4 acc[4][2];
; #pragma unroll
;                     for (int mt = 0; mt < 4; ++mt) { acc[mt][0] = (f32x4){0.f, 0.f, 0.f, 0.f}; acc[mt][1] = (f32x4){0.f, 0.f, 0.f, 0.f}; }
; #pragma unroll
;                     for (int kk = 0; kk < 6; ++kk)
; #pragma unroll
;                         for (int mt = 0; mt < 4; ++mt) {
;                             const bf16x8 af = *(const LAS bf16x8*)(lds + XC + (16 * mt + fr) * TR + (32 * kk + 8 * fq) * 2);
;                             acc[mt][0] = __builtin_amdgcn_mfma_f32_16x16x32_bf16(af, Bf[u][kk], acc[mt][0], 0, 0, 0);
;                             acc[mt][1] = __builtin_amdgcn_mfma_f32_16x16x32_bf16(af, Bf[2 + u][kk], acc[mt][1], 0, 0, 0);
;                         }
;                     const int ch = chb + 16 * u + fr;
;                     const float ba = gb[ch], bx = gb[192 + ch], sp = gb[384 + ch];
.Lconv_x_done:
	s_or_b64 exec, exec, s[2:3]
	s_waitcnt lgkmcnt(0)
	s_barrier
	ds_read_b128 v[120:123], v204 offset:26880
	ds_read_b128 v[124:127], v204 offset:33280
	ds_read_b128 v[128:131], v204 offset:39680
	ds_read_b128 v[132:135], v204 offset:46080
	ds_read_b128 v[226:229], v204 offset:26944
	s_waitcnt lgkmcnt(4)
	v_mfma_f32_16x16x32_bf16 v[148:151], v[120:123], v[0:3], 0
	v_mfma_f32_16x16x32_bf16 v[144:147], v[120:123], v[48:51], 0
	ds_read_b128 v[230:233], v204 offset:33344
	s_waitcnt lgkmcnt(4)
	v_mfma_f32_16x16x32_bf16 v[140:143], v[124:127], v[0:3], 0
	v_mfma_f32_16x16x32_bf16 v[136:139], v[124:127], v[48:51], 0
	ds_read_b128 v[120:123], v204 offset:39744
	s_waitcnt lgkmcnt(4)
	v_mfma_f32_16x16x32_bf16 v[214:217], v[128:131], v[0:3], 0
	v_mfma_f32_16x16x32_bf16 v[210:213], v[128:131], v[48:51], 0
	ds_read_b128 v[124:127], v204 offset:46144
	s_waitcnt lgkmcnt(4)
	v_mfma_f32_16x16x32_bf16 v[218:221], v[132:135], v[0:3], 0
	v_mfma_f32_16x16x32_bf16 v[222:225], v[132:135], v[48:51], 0
	ds_read_b128 v[128:131], v204 offset:27008
	s_waitcnt lgkmcnt(4)
	v_mfma_f32_16x16x32_bf16 v[148:151], v[226:229], v[4:7], v[148:151]
	v_mfma_f32_16x16x32_bf16 v[144:147], v[226:229], v[52:55], v[144:147]
	ds_read_b128 v[132:135], v204 offset:33408
	s_waitcnt lgkmcnt(4)
	v_mfma_f32_16x16x32_bf16 v[140:143], v[230:233], v[4:7], v[140:143]
	v_mfma_f32_16x16x32_bf16 v[136:139], v[230:233], v[52:55], v[136:139]
	ds_read_b128 v[226:229], v204 offset:39808
	s_waitcnt lgkmcnt(4)
	v_mfma_f32_16x16x32_bf16 v[214:217], v[120:123], v[4:7], v[214:217]
	v_mfma_f32_16x16x32_bf16 v[210:213], v[120:123], v[52:55], v[210:213]
	ds_read_b128 v[230:233], v204 offset:46208
	s_waitcnt lgkmcnt(4)
	v_mfma_f32_16x16x32_bf16 v[218:221], v[124:127], v[4:7], v[218:221]
	v_mfma_f32_16x16x32_bf16 v[222:225], v[124:127], v[52:55], v[222:225]
	ds_read_b128 v[120:123], v204 offset:27072
	s_waitcnt lgkmcnt(4)
	v_mfma_f32_16x16x32_bf16 v[148:151], v[128:131], v[8:11], v[148:151]
	v_mfma_f32_16x16x32_bf16 v[144:147], v[128:131], v[56:59], v[144:147]
	ds_read_b128 v[124:127], v204 offset:33472
	s_waitcnt lgkmcnt(4)
	v_mfma_f32_16x16x32_bf16 v[140:143], v[132:135], v[8:11], v[140:143]
	v_mfma_f32_16x16x32_bf16 v[136:139], v[132:135], v[56:59], v[136:139]
	ds_read_b128 v[128:131], v204 offset:39872
	s_waitcnt lgkmcnt(4)
	v_mfma_f32_16x16x32_bf16 v[214:217], v[226:229], v[8:11], v[214:217]
	v_mfma_f32_16x16x32_bf16 v[210:213], v[226:229], v[56:59], v[210:213]
	ds_read_b128 v[132:135], v204 offset:46272
	s_waitcnt lgkmcnt(4)
	v_mfma_f32_16x16x32_bf16 v[218:221], v[230:233], v[8:11], v[218:221]
	v_mfma_f32_16x16x32_bf16 v[222:225], v[230:233], v[56:59], v[222:225]
	ds_read_b128 v[226:229], v204 offset:27136
	s_waitcnt lgkmcnt(4)
	v_mfma_f32_16x16x32_bf16 v[148:151], v[120:123], v[12:15], v[148:151]
	v_mfma_f32_16x16x32_bf16 v[144:147], v[120:123], v[60:63], v[144:147]
	ds_read_b128 v[230:233], v204 offset:33536
	s_waitcnt lgkmcnt(4)
	v_mfma_f32_16x16x32_bf16 v[140:143], v[124:127], v[12:15], v[140:143]
	v_mfma_f32_16x16x32_bf16 v[136:139], v[124:127], v[60:63], v[136:139]
	ds_read_b128 v[120:123], v204 offset:39936
	s_waitcnt lgkmcnt(4)
	v_mfma_f32_16x16x32_bf16 v[214:217], v[128:131], v[12:15], v[214:217]
	v_mfma_f32_16x16x32_bf16 v[210:213], v[128:131], v[60:63], v[210:213]
	ds_read_b128 v[124:127], v204 offset:46336
	s_waitcnt lgkmcnt(4)
	v_mfma_f32_16x16x32_bf16 v[218:221], v[132:135], v[12:15], v[218:221]
	v_mfma_f32_16x16x32_bf16 v[222:225], v[132:135], v[60:63], v[222:225]
	ds_read_b128 v[128:131], v204 offset:27200
	s_waitcnt lgkmcnt(4)
	v_mfma_f32_16x16x32_bf16 v[148:151], v[226:229], v[16:19], v[148:151]
	v_mfma_f32_16x16x32_bf16 v[144:147], v[226:229], v[64:67], v[144:147]
	ds_read_b128 v[132:135], v204 offset:33600
	s_waitcnt lgkmcnt(4)
	v_mfma_f32_16x16x32_bf16 v[140:143], v[230:233], v[16:19], v[140:143]
	v_mfma_f32_16x16x32_bf16 v[136:139], v[230:233], v[64:67], v[136:139]
	s_waitcnt lgkmcnt(3)
	v_mfma_f32_16x16x32_bf16 v[214:217], v[120:123], v[16:19], v[214:217]
	v_mfma_f32_16x16x32_bf16 v[210:213], v[120:123], v[64:67], v[210:213]
	s_waitcnt lgkmcnt(2)
	v_mfma_f32_16x16x32_bf16 v[218:221], v[124:127], v[16:19], v[218:221]
	v_mfma_f32_16x16x32_bf16 v[222:225], v[124:127], v[64:67], v[222:225]
	s_waitcnt lgkmcnt(1)
	v_mfma_f32_16x16x32_bf16 v[148:151], v[128:131], v[20:23], v[148:151]
	v_mfma_f32_16x16x32_bf16 v[144:147], v[128:131], v[68:71], v[144:147]
	s_waitcnt lgkmcnt(0)
	v_mfma_f32_16x16x32_bf16 v[140:143], v[132:135], v[20:23], v[140:143]
	v_mfma_f32_16x16x32_bf16 v[136:139], v[132:135], v[68:71], v[136:139]
	ds_read_b128 v[120:123], v204 offset:40000
	s_nop 1
	ds_read_b128 v[128:131], v204 offset:46400
	ds_read2st64_b32 v[170:171], v184 offset1:3
	ds_read_b32 v205, v184 offset:1536
	ds_read_u16 v226, v194 offset:26880
	ds_read_u16 v227, v194 offset:27280
	ds_read_u16 v228, v194 offset:27680
	ds_read_u16 v229, v194 offset:28080
	ds_read_u16 v230, v194 offset:33280
	ds_read_u16 v231, v194 offset:33680
	ds_read_u16 v232, v194 offset:34080
	ds_read_u16 v233, v194 offset:34480
	ds_read_u16 v234, v194 offset:39680
	ds_read_u16 v235, v194 offset:40080
	ds_read_u16 v236, v194 offset:40480
	ds_read_u16 v237, v194 offset:40880
	ds_read_u16 v238, v194 offset:46080
	ds_read_u16 v239, v194 offset:46480
	ds_read_u16 v240, v194 offset:46880
	ds_read_u16 v241, v194 offset:47280
	s_waitcnt lgkmcnt(15)
; #define LAS __attribute__((address_space(3)))
; DI void phase_rglru(const Params& p, unsigned char* shm) {
;     ...
;                     const float ba = gb[ch], bx = gb[192 + ch], sp = gb[384 + ch];
; #pragma unroll
;                     for (int mt = 0; mt < 4; ++mt)
; #pragma unroll
;                         for (int j = 0; j < 4; ++j) {
;                             const int t = 16 * mt + 4 * fq + j;
;                             const float ea = 1.f + __expf(fminf(-(acc[mt][0][j] + ba), 40.f)), ex = 1.f + __expf(fminf(-(acc[mt][1][j] + bx), 40.f));
;                             const float inv = __builtin_amdgcn_rcpf(ea * ex);
;                             const float r = inv * ex, ig = inv * ea;
;                             const float av = __expf(r * sp), om = 1.f - av;
;                             const float xcv = __uint_as_float((unsigned)*(const LAS bf16_t*)(lds + XC + t * TR + ch * 2) << 16);
;                             const float bt = __builtin_amdgcn_sqrtf(fmaxf(om * (1.f + av), 0.f)) * (ig * xcv);
	v_mov_b32_e32 v242, 0xbfb8aa3b
	v_mov_b32_e32 v243, 0x4266d4ca
	v_mul_f32_e32 v170, v242, v170
	v_mul_f32_e32 v171, v242, v171
	v_mul_f32_e32 v205, 0x3fb8aa3b, v205
	v_mfma_f32_16x16x32_bf16 v[124:127], v[120:123], v[20:23], v[214:217]
	v_mfma_f32_16x16x32_bf16 v[120:123], v[120:123], v[68:71], v[210:213]
	v_mfma_f32_16x16x32_bf16 v[132:135], v[128:131], v[20:23], v[218:221]
	v_mfma_f32_16x16x32_bf16 v[128:131], v[128:131], v[68:71], v[222:225]
	v_pk_fma_f32 v[148:149], v[148:149], v[242:243], v[170:171] op_sel_hi:[1,0,0]
	v_pk_fma_f32 v[144:145], v[144:145], v[242:243], v[170:171] op_sel:[0,0,1] op_sel_hi:[1,0,1]
	v_pk_fma_f32 v[150:151], v[150:151], v[242:243], v[170:171] op_sel_hi:[1,0,0]
	v_pk_fma_f32 v[146:147], v[146:147], v[242:243], v[170:171] op_sel:[0,0,1] op_sel_hi:[1,0,1]
	v_pk_fma_f32 v[140:141], v[140:141], v[242:243], v[170:171] op_sel_hi:[1,0,0]
	v_pk_fma_f32 v[136:137], v[136:137], v[242:243], v[170:171] op_sel:[0,0,1] op_sel_hi:[1,0,1]
	v_pk_fma_f32 v[142:143], v[142:143], v[242:243], v[170:171] op_sel_hi:[1,0,0]
	v_pk_fma_f32 v[138:139], v[138:139], v[242:243], v[170:171] op_sel:[0,0,1] op_sel_hi:[1,0,1]
	v_min_f32_e32 v148, v243, v148
	v_min_f32_e32 v149, v243, v149
	v_min_f32_e32 v144, v243, v144
	v_min_f32_e32 v145, v243, v145
	v_min_f32_e32 v150, v243, v150
	v_min_f32_e32 v151, v243, v151
	v_min_f32_e32 v146, v243, v146
	v_min_f32_e32 v147, v243, v147
	v_min_f32_e32 v140, v243, v140
	v_min_f32_e32 v141, v243, v141
	v_min_f32_e32 v136, v243, v136
	v_min_f32_e32 v137, v243, v137
	v_min_f32_e32 v142, v243, v142
	v_min_f32_e32 v143, v243, v143
	v_min_f32_e32 v138, v243, v138
	v_min_f32_e32 v139, v243, v139
	v_exp_f32_e32 v148, v148
	v_exp_f32_e32 v149, v149
	v_exp_f32_e32 v144, v144
	v_exp_f32_e32 v145, v145
	v_exp_f32_e32 v150, v150
	v_exp_f32_e32 v151, v151
	v_exp_f32_e32 v146, v146
	v_exp_f32_e32 v147, v147
	v_exp_f32_e32 v140, v140
	v_exp_f32_e32 v141, v141
	v_exp_f32_e32 v136, v136
	v_exp_f32_e32 v137, v137
	v_exp_f32_e32 v142, v142
	v_exp_f32_e32 v143, v143
	v_exp_f32_e32 v138, v138
	v_exp_f32_e32 v139, v139
	v_pk_add_f32 v[148:149], v[148:149], 1.0 op_sel_hi:[1,0]
	v_pk_add_f32 v[144:145], v[144:145], 1.0 op_sel_hi:[1,0]
	v_pk_add_f32 v[150:151], v[150:151], 1.0 op_sel_hi:[1,0]
	v_pk_add_f32 v[146:147], v[146:147], 1.0 op_sel_hi:[1,0]
	v_pk_add_f32 v[140:141], v[140:141], 1.0 op_sel_hi:[1,0]
	v_pk_add_f32 v[136:137], v[136:137], 1.0 op_sel_hi:[1,0]
	v_pk_add_f32 v[142:143], v[142:143], 1.0 op_sel_hi:[1,0]
	v_pk_add_f32 v[138:139], v[138:139], 1.0 op_sel_hi:[1,0]
	v_pk_mul_f32 v[210:211], v[148:149], v[144:145]
	v_pk_mul_f32 v[212:213], v[150:151], v[146:147]
	v_pk_mul_f32 v[214:215], v[140:141], v[136:137]
	v_pk_mul_f32 v[216:217], v[142:143], v[138:139]
	v_rcp_f32_e32 v210, v210
	v_rcp_f32_e32 v211, v211
	v_rcp_f32_e32 v212, v212
	v_rcp_f32_e32 v213, v213
	v_rcp_f32_e32 v214, v214
	v_rcp_f32_e32 v215, v215
	v_rcp_f32_e32 v216, v216
	v_rcp_f32_e32 v217, v217
	v_pk_mul_f32 v[144:145], v[144:145], v[210:211]
	v_pk_mul_f32 v[148:149], v[148:149], v[210:211]
	v_pk_mul_f32 v[146:147], v[146:147], v[212:213]
	v_pk_mul_f32 v[150:151], v[150:151], v[212:213]
	v_pk_mul_f32 v[136:137], v[136:137], v[214:215]
	v_pk_mul_f32 v[140:141], v[140:141], v[214:215]
	v_pk_mul_f32 v[138:139], v[138:139], v[216:217]
	v_pk_mul_f32 v[142:143], v[142:143], v[216:217]
	v_pk_mul_f32 v[144:145], v[144:145], v[204:205] op_sel:[0,1] op_sel_hi:[1,1]
	v_pk_mul_f32 v[146:147], v[146:147], v[204:205] op_sel:[0,1] op_sel_hi:[1,1]
	v_pk_mul_f32 v[136:137], v[136:137], v[204:205] op_sel:[0,1] op_sel_hi:[1,1]
	v_pk_mul_f32 v[138:139], v[138:139], v[204:205] op_sel:[0,1] op_sel_hi:[1,1]
	v_exp_f32_e32 v144, v144
	v_exp_f32_e32 v145, v145
	v_exp_f32_e32 v146, v146
	v_exp_f32_e32 v147, v147
	v_exp_f32_e32 v136, v136
	v_exp_f32_e32 v137, v137
	v_exp_f32_e32 v138, v138
	v_exp_f32_e32 v139, v139
	v_pk_add_f32 v[210:211], v[144:145], 1.0 op_sel_hi:[1,0] neg_lo:[1,0] neg_hi:[1,0]
	v_pk_add_f32 v[144:145], v[144:145], 1.0 op_sel_hi:[1,0]
	v_pk_add_f32 v[212:213], v[146:147], 1.0 op_sel_hi:[1,0] neg_lo:[1,0] neg_hi:[1,0]
	v_pk_add_f32 v[146:147], v[146:147], 1.0 op_sel_hi:[1,0]
	v_pk_add_f32 v[214:215], v[136:137], 1.0 op_sel_hi:[1,0] neg_lo:[1,0] neg_hi:[1,0]
	v_pk_add_f32 v[136:137], v[136:137], 1.0 op_sel_hi:[1,0]
	v_pk_add_f32 v[216:217], v[138:139], 1.0 op_sel_hi:[1,0] neg_lo:[1,0] neg_hi:[1,0]
	v_pk_add_f32 v[138:139], v[138:139], 1.0 op_sel_hi:[1,0]
	v_pk_mul_f32 v[144:145], v[210:211], v[144:145]
	v_pk_mul_f32 v[146:147], v[212:213], v[146:147]
	v_pk_mul_f32 v[136:137], v[214:215], v[136:137]
	v_pk_mul_f32 v[138:139], v[216:217], v[138:139]
	v_max_f32_e32 v144, 0, v144
	v_max_f32_e32 v145, 0, v145
	v_max_f32_e32 v146, 0, v146
	v_max_f32_e32 v147, 0, v147
	v_max_f32_e32 v136, 0, v136
	v_max_f32_e32 v137, 0, v137
	v_max_f32_e32 v138, 0, v138
	v_max_f32_e32 v139, 0, v139
	v_sqrt_f32_e32 v144, v144
	v_sqrt_f32_e32 v145, v145
	v_sqrt_f32_e32 v146, v146
	v_sqrt_f32_e32 v147, v147
	v_sqrt_f32_e32 v136, v136
	v_sqrt_f32_e32 v137, v137
	v_sqrt_f32_e32 v138, v138
	v_sqrt_f32_e32 v139, v139
	s_waitcnt lgkmcnt(0)
; #define LAS __attribute__((address_space(3)))
; DI unsigned pk2(float a, float b) { f32x2 v = {a, b}; bf2_t r = __builtin_convertvector(v, bf2_t); return __builtin_bit_cast(unsigned, r); }
; DI void phase_rglru(const Params& p, unsigned char* shm) {
;     ...
;                             const float ea = 1.f + __expf(fminf(-(acc[mt][0][j] + ba), 40.f)), ex = 1.f + __expf(fminf(-(acc[mt][1][j] + bx), 40.f));
;                             const float inv = __builtin_amdgcn_rcpf(ea * ex);
;                             const float r = inv * ex, ig = inv * ea;
;                             const float av = __expf(r * sp), om = 1.f - av;
;                             const float xcv = __uint_as_float((unsigned)*(const LAS bf16_t*)(lds + XC + t * TR + ch * 2) << 16);
;                             const float bt = __builtin_amdgcn_sqrtf(fmaxf(om * (1.f + av), 0.f)) * (ig * xcv);
;                             *(LAS bf16_t*)(lds + LAo + t * TR + ch * 2) = (bf16_t)(pk2(om, 0.f) & 0xffffu);
;                             *(LAS bf16_t*)(lds + BTo + t * TR + ch * 2) = (bf16_t)(pk2(bt, 0.f) & 0xffffu);
	v_lshlrev_b32_e32 v226, 16, v226
	v_lshlrev_b32_e32 v227, 16, v227
	v_lshlrev_b32_e32 v228, 16, v228
	v_lshlrev_b32_e32 v229, 16, v229
	v_lshlrev_b32_e32 v230, 16, v230
	v_lshlrev_b32_e32 v231, 16, v231
	v_lshlrev_b32_e32 v232, 16, v232
	v_lshlrev_b32_e32 v233, 16, v233
	v_pk_mul_f32 v[148:149], v[148:149], v[226:227]
	v_pk_mul_f32 v[150:151], v[150:151], v[228:229]
	v_pk_mul_f32 v[140:141], v[140:141], v[230:231]
	v_pk_mul_f32 v[142:143], v[142:143], v[232:233]
	v_pk_mul_f32 v[148:149], v[148:149], v[144:145]
	v_pk_mul_f32 v[150:151], v[150:151], v[146:147]
	v_pk_mul_f32 v[140:141], v[140:141], v[136:137]
	v_pk_mul_f32 v[142:143], v[142:143], v[138:139]
	v_cvt_pk_bf16_f32 v210, v210, v211
	v_cvt_pk_bf16_f32 v148, v148, v149
	v_cvt_pk_bf16_f32 v212, v212, v213
	v_cvt_pk_bf16_f32 v150, v150, v151
	v_cvt_pk_bf16_f32 v214, v214, v215
	v_cvt_pk_bf16_f32 v140, v140, v141
	v_cvt_pk_bf16_f32 v216, v216, v217
	v_cvt_pk_bf16_f32 v142, v142, v143
	ds_write_b16 v195, v210
	ds_write_b16_d16_hi v195, v210 offset:400
	ds_write_b16 v196, v148
	ds_write_b16_d16_hi v196, v148 offset:400
	ds_write_b16 v195, v212 offset:800
	ds_write_b16_d16_hi v195, v212 offset:1200
	ds_write_b16 v196, v150 offset:800
	ds_write_b16_d16_hi v196, v150 offset:1200
	ds_write_b16 v195, v214 offset:6400
	ds_write_b16_d16_hi v195, v214 offset:6800
	ds_write_b16 v196, v140 offset:6400
	ds_write_b16_d16_hi v196, v140 offset:6800
	ds_write_b16 v195, v216 offset:7200
	ds_write_b16_d16_hi v195, v216 offset:7600
	ds_write_b16 v196, v142 offset:7200
	ds_write_b16_d16_hi v196, v142 offset:7600
	v_pk_fma_f32 v[124:125], v[124:125], v[242:243], v[170:171] op_sel_hi:[1,0,0]
	v_pk_fma_f32 v[120:121], v[120:121], v[242:243], v[170:171] op_sel:[0,0,1] op_sel_hi:[1,0,1]
	v_pk_fma_f32 v[126:127], v[126:127], v[242:243], v[170:171] op_sel_hi:[1,0,0]
	v_pk_fma_f32 v[122:123], v[122:123], v[242:243], v[170:171] op_sel:[0,0,1] op_sel_hi:[1,0,1]
	v_pk_fma_f32 v[132:133], v[132:133], v[242:243], v[170:171] op_sel_hi:[1,0,0]
	v_pk_fma_f32 v[128:129], v[128:129], v[242:243], v[170:171] op_sel:[0,0,1] op_sel_hi:[1,0,1]
	v_pk_fma_f32 v[134:135], v[134:135], v[242:243], v[170:171] op_sel_hi:[1,0,0]
	v_pk_fma_f32 v[130:131], v[130:131], v[242:243], v[170:171] op_sel:[0,0,1] op_sel_hi:[1,0,1]
	v_min_f32_e32 v124, v243, v124
	v_min_f32_e32 v125, v243, v125
	v_min_f32_e32 v120, v243, v120
	v_min_f32_e32 v121, v243, v121
	v_min_f32_e32 v126, v243, v126
	v_min_f32_e32 v127, v243, v127
	v_min_f32_e32 v122, v243, v122
	v_min_f32_e32 v123, v243, v123
	v_min_f32_e32 v132, v243, v132
	v_min_f32_e32 v133, v243, v133
	v_min_f32_e32 v128, v243, v128
	v_min_f32_e32 v129, v243, v129
	v_min_f32_e32 v134, v243, v134
	v_min_f32_e32 v135, v243, v135
	v_min_f32_e32 v130, v243, v130
	v_min_f32_e32 v131, v243, v131
	v_exp_f32_e32 v124, v124
	v_exp_f32_e32 v125, v125
	v_exp_f32_e32 v120, v120
	v_exp_f32_e32 v121, v121
	v_exp_f32_e32 v126, v126
	v_exp_f32_e32 v127, v127
	v_exp_f32_e32 v122, v122
	v_exp_f32_e32 v123, v123
	v_exp_f32_e32 v132, v132
	v_exp_f32_e32 v133, v133
	v_exp_f32_e32 v128, v128
	v_exp_f32_e32 v129, v129
	v_exp_f32_e32 v134, v134
	v_exp_f32_e32 v135, v135
	v_exp_f32_e32 v130, v130
	v_exp_f32_e32 v131, v131
	v_pk_add_f32 v[124:125], v[124:125], 1.0 op_sel_hi:[1,0]
	v_pk_add_f32 v[120:121], v[120:121], 1.0 op_sel_hi:[1,0]
	v_pk_add_f32 v[126:127], v[126:127], 1.0 op_sel_hi:[1,0]
	v_pk_add_f32 v[122:123], v[122:123], 1.0 op_sel_hi:[1,0]
	v_pk_add_f32 v[132:133], v[132:133], 1.0 op_sel_hi:[1,0]
	v_pk_add_f32 v[128:129], v[128:129], 1.0 op_sel_hi:[1,0]
	v_pk_add_f32 v[134:135], v[134:135], 1.0 op_sel_hi:[1,0]
	v_pk_add_f32 v[130:131], v[130:131], 1.0 op_sel_hi:[1,0]
	v_pk_mul_f32 v[210:211], v[124:125], v[120:121]
	v_pk_mul_f32 v[212:213], v[126:127], v[122:123]
	v_pk_mul_f32 v[214:215], v[132:133], v[128:129]
	v_pk_mul_f32 v[216:217], v[134:135], v[130:131]
	v_rcp_f32_e32 v210, v210
	v_rcp_f32_e32 v211, v211
	v_rcp_f32_e32 v212, v212
	v_rcp_f32_e32 v213, v213
	v_rcp_f32_e32 v214, v214
	v_rcp_f32_e32 v215, v215
	v_rcp_f32_e32 v216, v216
	v_rcp_f32_e32 v217, v217
	v_pk_mul_f32 v[120:121], v[120:121], v[210:211]
	v_pk_mul_f32 v[124:125], v[124:125], v[210:211]
	v_pk_mul_f32 v[122:123], v[122:123], v[212:213]
	v_pk_mul_f32 v[126:127], v[126:127], v[212:213]
	v_pk_mul_f32 v[128:129], v[128:129], v[214:215]
	v_pk_mul_f32 v[132:133], v[132:133], v[214:215]
	v_pk_mul_f32 v[130:131], v[130:131], v[216:217]
	v_pk_mul_f32 v[134:135], v[134:135], v[216:217]
	v_pk_mul_f32 v[120:121], v[120:121], v[204:205] op_sel:[0,1] op_sel_hi:[1,1]
	v_pk_mul_f32 v[122:123], v[122:123], v[204:205] op_sel:[0,1] op_sel_hi:[1,1]
	v_pk_mul_f32 v[128:129], v[128:129], v[204:205] op_sel:[0,1] op_sel_hi:[1,1]
	v_pk_mul_f32 v[130:131], v[130:131], v[204:205] op_sel:[0,1] op_sel_hi:[1,1]
	v_exp_f32_e32 v120, v120
	v_exp_f32_e32 v121, v121
	v_exp_f32_e32 v122, v122
	v_exp_f32_e32 v123, v123
	v_exp_f32_e32 v128, v128
	v_exp_f32_e32 v129, v129
	v_exp_f32_e32 v130, v130
	v_exp_f32_e32 v131, v131
	v_pk_add_f32 v[210:211], v[120:121], 1.0 op_sel_hi:[1,0] neg_lo:[1,0] neg_hi:[1,0]
	v_pk_add_f32 v[120:121], v[120:121], 1.0 op_sel_hi:[1,0]
	v_pk_add_f32 v[212:213], v[122:123], 1.0 op_sel_hi:[1,0] neg_lo:[1,0] neg_hi:[1,0]
	v_pk_add_f32 v[122:123], v[122:123], 1.0 op_sel_hi:[1,0]
	v_pk_add_f32 v[214:215], v[128:129], 1.0 op_sel_hi:[1,0] neg_lo:[1,0] neg_hi:[1,0]
	v_pk_add_f32 v[128:129], v[128:129], 1.0 op_sel_hi:[1,0]
	v_pk_add_f32 v[216:217], v[130:131], 1.0 op_sel_hi:[1,0] neg_lo:[1,0] neg_hi:[1,0]
	v_pk_add_f32 v[130:131], v[130:131], 1.0 op_sel_hi:[1,0]
	v_pk_mul_f32 v[120:121], v[210:211], v[120:121]
	v_pk_mul_f32 v[122:123], v[212:213], v[122:123]
; #define LAS __attribute__((address_space(3)))
; DI unsigned pk2(float a, float b) { f32x2 v = {a, b}; bf2_t r = __builtin_convertvector(v, bf2_t); return __builtin_bit_cast(unsigned, r); }
; DI void phase_rglru(const Params& p, unsigned char* shm) {
;     ...
;                 for (int u = 0; u < 2; ++u) {
;                     if (u == 1 && w >= 4) break;
;                     f32x4 acc[4][2];
; #pragma unroll
;                     for (int mt = 0; mt < 4; ++mt) { acc[mt][0] = (f32x4){0.f, 0.f, 0.f, 0.f}; acc[mt][1] = (f32x4){0.f, 0.f, 0.f, 0.f}; }
; #pragma unroll
;                     for (int kk = 0; kk < 6; ++kk)
; #pragma unroll
;                         for (int mt = 0; mt < 4; ++mt) {
;                             const bf16x8 af = *(const LAS bf16x8*)(lds + XC + (16 * mt + fr) * TR + (32 * kk + 8 * fq) * 2);
;                             acc[mt][0] = __builtin_amdgcn_mfma_f32_16x16x32_bf16(af, Bf[u][kk], acc[mt][0], 0, 0, 0);
;                             acc[mt][1] = __builtin_amdgcn_mfma_f32_16x16x32_bf16(af, Bf[2 + u][kk], acc[mt][1], 0, 0, 0);
;                         }
;     ...
;                             const float ea = 1.f + __expf(fminf(-(acc[mt][0][j] + ba), 40.f)), ex = 1.f + __expf(fminf(-(acc[mt][1][j] + bx), 40.f));
;                             const float inv = __builtin_amdgcn_rcpf(ea * ex);
;                             const float r = inv * ex, ig = inv * ea;
;                             const float av = __expf(r * sp), om = 1.f - av;
;                             const float xcv = __uint_as_float((unsigned)*(const LAS bf16_t*)(lds + XC + t * TR + ch * 2) << 16);
;                             const float bt = __builtin_amdgcn_sqrtf(fmaxf(om * (1.f + av), 0.f)) * (ig * xcv);
;                             *(LAS bf16_t*)(lds + LAo + t * TR + ch * 2) = (bf16_t)(pk2(om, 0.f) & 0xffffu);
;                             *(LAS bf16_t*)(lds + BTo + t * TR + ch * 2) = (bf16_t)(pk2(bt, 0.f) & 0xffffu);
;                         }
	v_pk_mul_f32 v[128:129], v[214:215], v[128:129]
	v_pk_mul_f32 v[130:131], v[216:217], v[130:131]
	v_max_f32_e32 v120, 0, v120
	v_max_f32_e32 v121, 0, v121
	v_max_f32_e32 v122, 0, v122
	v_max_f32_e32 v123, 0, v123
	v_max_f32_e32 v128, 0, v128
	v_max_f32_e32 v129, 0, v129
	v_max_f32_e32 v130, 0, v130
	v_max_f32_e32 v131, 0, v131
	v_sqrt_f32_e32 v120, v120
	v_sqrt_f32_e32 v121, v121
	v_sqrt_f32_e32 v122, v122
	v_sqrt_f32_e32 v123, v123
	v_sqrt_f32_e32 v128, v128
	v_sqrt_f32_e32 v129, v129
	v_sqrt_f32_e32 v130, v130
	v_sqrt_f32_e32 v131, v131
	v_lshlrev_b32_e32 v234, 16, v234
	v_lshlrev_b32_e32 v235, 16, v235
	v_lshlrev_b32_e32 v236, 16, v236
	v_lshlrev_b32_e32 v237, 16, v237
	v_lshlrev_b32_e32 v238, 16, v238
	v_lshlrev_b32_e32 v239, 16, v239
	v_lshlrev_b32_e32 v240, 16, v240
	v_lshlrev_b32_e32 v241, 16, v241
	v_pk_mul_f32 v[124:125], v[124:125], v[234:235]
	v_pk_mul_f32 v[126:127], v[126:127], v[236:237]
	v_pk_mul_f32 v[132:133], v[132:133], v[238:239]
	v_pk_mul_f32 v[134:135], v[134:135], v[240:241]
	v_pk_mul_f32 v[124:125], v[124:125], v[120:121]
	v_pk_mul_f32 v[126:127], v[126:127], v[122:123]
	v_pk_mul_f32 v[132:133], v[132:133], v[128:129]
	v_pk_mul_f32 v[134:135], v[134:135], v[130:131]
	v_cvt_pk_bf16_f32 v210, v210, v211
	v_cvt_pk_bf16_f32 v124, v124, v125
	v_cvt_pk_bf16_f32 v212, v212, v213
	v_cvt_pk_bf16_f32 v126, v126, v127
	v_cvt_pk_bf16_f32 v214, v214, v215
	v_cvt_pk_bf16_f32 v132, v132, v133
	v_cvt_pk_bf16_f32 v216, v216, v217
	v_cvt_pk_bf16_f32 v134, v134, v135
	ds_write_b16 v195, v210 offset:12800
	ds_write_b16_d16_hi v195, v210 offset:13200
	ds_write_b16 v196, v124 offset:12800
	ds_write_b16_d16_hi v196, v124 offset:13200
	ds_write_b16 v195, v212 offset:13600
	ds_write_b16_d16_hi v195, v212 offset:14000
	ds_write_b16 v196, v126 offset:13600
	ds_write_b16_d16_hi v196, v126 offset:14000
	ds_write_b16 v195, v214 offset:19200
	ds_write_b16_d16_hi v195, v214 offset:19600
	ds_write_b16 v196, v132 offset:19200
	ds_write_b16_d16_hi v196, v132 offset:19600
	ds_write_b16 v195, v216 offset:20000
	ds_write_b16_d16_hi v195, v216 offset:20400
	ds_write_b16 v196, v134 offset:20000
	ds_write_b16_d16_hi v196, v134 offset:20400
	s_andn2_b64 vcc, exec, s[12:13]
	s_cbranch_vccnz .Lgates_b
	ds_read_b128 v[120:123], v204 offset:26880
	ds_read_b128 v[124:127], v204 offset:33280
	ds_read_b128 v[128:131], v204 offset:26944
	ds_read_b128 v[132:135], v204 offset:33344
	ds_read_b128 v[226:229], v204 offset:27008
	s_waitcnt lgkmcnt(4)
	v_mfma_f32_16x16x32_bf16 v[148:151], v[120:123], v[24:27], 0
	v_mfma_f32_16x16x32_bf16 v[144:147], v[120:123], v[72:75], 0
	ds_read_b128 v[230:233], v204 offset:33408
	s_waitcnt lgkmcnt(4)
	v_mfma_f32_16x16x32_bf16 v[140:143], v[124:127], v[24:27], 0
	v_mfma_f32_16x16x32_bf16 v[136:139], v[124:127], v[72:75], 0
	ds_read_b128 v[120:123], v204 offset:27072
	s_waitcnt lgkmcnt(4)
	v_mfma_f32_16x16x32_bf16 v[148:151], v[128:131], v[28:31], v[148:151]
	v_mfma_f32_16x16x32_bf16 v[144:147], v[128:131], v[76:79], v[144:147]
	ds_read_b128 v[124:127], v204 offset:33472
	s_waitcnt lgkmcnt(4)
	v_mfma_f32_16x16x32_bf16 v[140:143], v[132:135], v[28:31], v[140:143]
	v_mfma_f32_16x16x32_bf16 v[136:139], v[132:135], v[76:79], v[136:139]
	ds_read_b128 v[128:131], v204 offset:27136
	s_waitcnt lgkmcnt(4)
	v_mfma_f32_16x16x32_bf16 v[148:151], v[226:229], v[32:35], v[148:151]
	v_mfma_f32_16x16x32_bf16 v[144:147], v[226:229], v[80:83], v[144:147]
	ds_read_b128 v[132:135], v204 offset:33536
	s_waitcnt lgkmcnt(4)
	v_mfma_f32_16x16x32_bf16 v[140:143], v[230:233], v[32:35], v[140:143]
	v_mfma_f32_16x16x32_bf16 v[136:139], v[230:233], v[80:83], v[136:139]
	ds_read_b128 v[226:229], v204 offset:27200
	s_waitcnt lgkmcnt(4)
	v_mfma_f32_16x16x32_bf16 v[148:151], v[120:123], v[36:39], v[148:151]
	v_mfma_f32_16x16x32_bf16 v[144:147], v[120:123], v[84:87], v[144:147]
	ds_read_b128 v[230:233], v204 offset:33600
	s_waitcnt lgkmcnt(4)
	v_mfma_f32_16x16x32_bf16 v[140:143], v[124:127], v[36:39], v[140:143]
	v_mfma_f32_16x16x32_bf16 v[136:139], v[124:127], v[84:87], v[136:139]
	s_waitcnt lgkmcnt(3)
	v_mfma_f32_16x16x32_bf16 v[148:151], v[128:131], v[40:43], v[148:151]
	v_mfma_f32_16x16x32_bf16 v[144:147], v[128:131], v[88:91], v[144:147]
	s_waitcnt lgkmcnt(2)
	v_mfma_f32_16x16x32_bf16 v[140:143], v[132:135], v[40:43], v[140:143]
	v_mfma_f32_16x16x32_bf16 v[136:139], v[132:135], v[88:91], v[136:139]
	s_waitcnt lgkmcnt(1)
	v_mfma_f32_16x16x32_bf16 v[148:151], v[226:229], v[44:47], v[148:151]
	v_mfma_f32_16x16x32_bf16 v[144:147], v[226:229], v[92:95], v[144:147]
	s_waitcnt lgkmcnt(0)
	v_mfma_f32_16x16x32_bf16 v[140:143], v[230:233], v[44:47], v[140:143]
	v_mfma_f32_16x16x32_bf16 v[136:139], v[230:233], v[92:95], v[136:139]
	s_nop 1
	ds_read2st64_b32 v[170:171], v185 offset1:3
	ds_read_b32 v205, v185 offset:1536
	ds_read_u16 v226, v197 offset:26880
	ds_read_u16 v227, v197 offset:27280
	ds_read_u16 v228, v197 offset:27680
	ds_read_u16 v229, v197 offset:28080
	ds_read_u16 v230, v197 offset:33280
	ds_read_u16 v231, v197 offset:33680
	ds_read_u16 v232, v197 offset:34080
	ds_read_u16 v233, v197 offset:34480
	ds_read_u16 v234, v197 offset:39680
	ds_read_u16 v235, v197 offset:40080
	ds_read_u16 v236, v197 offset:40480
	ds_read_u16 v237, v197 offset:40880
	ds_read_u16 v238, v197 offset:46080
	ds_read_u16 v239, v197 offset:46480
	ds_read_u16 v240, v197 offset:46880
	ds_read_u16 v241, v197 offset:47280
	s_waitcnt lgkmcnt(15)
; #define LAS __attribute__((address_space(3)))
; DI unsigned pk2(float a, float b) { f32x2 v = {a, b}; bf2_t r = __builtin_convertvector(v, bf2_t); return __builtin_bit_cast(unsigned, r); }
; DI void phase_rglru(const Params& p, unsigned char* shm) {
;     ...
;                     const float ba = gb[ch], bx = gb[192 + ch], sp = gb[384 + ch];
; #pragma unroll
;                     for (int mt = 0; mt < 4; ++mt)
; #pragma unroll
;                         for (int j = 0; j < 4; ++j) {
;                             const int t = 16 * mt + 4 * fq + j;
;                             const float ea = 1.f + __expf(fminf(-(acc[mt][0][j] + ba), 40.f)), ex = 1.f + __expf(fminf(-(acc[mt][1][j] + bx), 40.f));
;                             const float inv = __builtin_amdgcn_rcpf(ea * ex);
;                             const float r = inv * ex, ig = inv * ea;
;                             const float av = __expf(r * sp), om = 1.f - av;
;                             const float xcv = __uint_as_float((unsigned)*(const LAS bf16_t*)(lds + XC + t * TR + ch * 2) << 16);
;                             const float bt = __builtin_amdgcn_sqrtf(fmaxf(om * (1.f + av), 0.f)) * (ig * xcv);
;                             *(LAS bf16_t*)(lds + LAo + t * TR + ch * 2) = (bf16_t)(pk2(om, 0.f) & 0xffffu);
;                             *(LAS bf16_t*)(lds + BTo + t * TR + ch * 2) = (bf16_t)(pk2(bt, 0.f) & 0xffffu);
	v_mov_b32_e32 v242, 0xbfb8aa3b
	v_mov_b32_e32 v243, 0x4266d4ca
	v_mul_f32_e32 v170, v242, v170
	v_mul_f32_e32 v171, v242, v171
	v_mul_f32_e32 v205, 0x3fb8aa3b, v205
	v_pk_fma_f32 v[148:149], v[148:149], v[242:243], v[170:171] op_sel_hi:[1,0,0]
	v_pk_fma_f32 v[144:145], v[144:145], v[242:243], v[170:171] op_sel:[0,0,1] op_sel_hi:[1,0,1]
	v_pk_fma_f32 v[150:151], v[150:151], v[242:243], v[170:171] op_sel_hi:[1,0,0]
	v_pk_fma_f32 v[146:147], v[146:147], v[242:243], v[170:171] op_sel:[0,0,1] op_sel_hi:[1,0,1]
	v_pk_fma_f32 v[140:141], v[140:141], v[242:243], v[170:171] op_sel_hi:[1,0,0]
	v_pk_fma_f32 v[136:137], v[136:137], v[242:243], v[170:171] op_sel:[0,0,1] op_sel_hi:[1,0,1]
	v_pk_fma_f32 v[142:143], v[142:143], v[242:243], v[170:171] op_sel_hi:[1,0,0]
	v_pk_fma_f32 v[138:139], v[138:139], v[242:243], v[170:171] op_sel:[0,0,1] op_sel_hi:[1,0,1]
	v_min_f32_e32 v148, v243, v148
	v_min_f32_e32 v149, v243, v149
	v_min_f32_e32 v144, v243, v144
	v_min_f32_e32 v145, v243, v145
	v_min_f32_e32 v150, v243, v150
	v_min_f32_e32 v151, v243, v151
	v_min_f32_e32 v146, v243, v146
	v_min_f32_e32 v147, v243, v147
	v_min_f32_e32 v140, v243, v140
	v_min_f32_e32 v141, v243, v141
	v_min_f32_e32 v136, v243, v136
	v_min_f32_e32 v137, v243, v137
	v_min_f32_e32 v142, v243, v142
	v_min_f32_e32 v143, v243, v143
	v_min_f32_e32 v138, v243, v138
	v_min_f32_e32 v139, v243, v139
	v_exp_f32_e32 v148, v148
	v_exp_f32_e32 v149, v149
	v_exp_f32_e32 v144, v144
	v_exp_f32_e32 v145, v145
	v_exp_f32_e32 v150, v150
	v_exp_f32_e32 v151, v151
	v_exp_f32_e32 v146, v146
	v_exp_f32_e32 v147, v147
	v_exp_f32_e32 v140, v140
	v_exp_f32_e32 v141, v141
	v_exp_f32_e32 v136, v136
	v_exp_f32_e32 v137, v137
	v_exp_f32_e32 v142, v142
	v_exp_f32_e32 v143, v143
	v_exp_f32_e32 v138, v138
	v_exp_f32_e32 v139, v139
	v_pk_add_f32 v[148:149], v[148:149], 1.0 op_sel_hi:[1,0]
	v_pk_add_f32 v[144:145], v[144:145], 1.0 op_sel_hi:[1,0]
	v_pk_add_f32 v[150:151], v[150:151], 1.0 op_sel_hi:[1,0]
	v_pk_add_f32 v[146:147], v[146:147], 1.0 op_sel_hi:[1,0]
	v_pk_add_f32 v[140:141], v[140:141], 1.0 op_sel_hi:[1,0]
	v_pk_add_f32 v[136:137], v[136:137], 1.0 op_sel_hi:[1,0]
	v_pk_add_f32 v[142:143], v[142:143], 1.0 op_sel_hi:[1,0]
	v_pk_add_f32 v[138:139], v[138:139], 1.0 op_sel_hi:[1,0]
	v_pk_mul_f32 v[210:211], v[148:149], v[144:145]
	v_pk_mul_f32 v[212:213], v[150:151], v[146:147]
	v_pk_mul_f32 v[214:215], v[140:141], v[136:137]
	v_pk_mul_f32 v[216:217], v[142:143], v[138:139]
	v_rcp_f32_e32 v210, v210
	v_rcp_f32_e32 v211, v211
	v_rcp_f32_e32 v212, v212
	v_rcp_f32_e32 v213, v213
	v_rcp_f32_e32 v214, v214
	v_rcp_f32_e32 v215, v215
	v_rcp_f32_e32 v216, v216
	v_rcp_f32_e32 v217, v217
	v_pk_mul_f32 v[144:145], v[144:145], v[210:211]
	v_pk_mul_f32 v[148:149], v[148:149], v[210:211]
	v_pk_mul_f32 v[146:147], v[146:147], v[212:213]
	v_pk_mul_f32 v[150:151], v[150:151], v[212:213]
	v_pk_mul_f32 v[136:137], v[136:137], v[214:215]
	v_pk_mul_f32 v[140:141], v[140:141], v[214:215]
	v_pk_mul_f32 v[138:139], v[138:139], v[216:217]
	v_pk_mul_f32 v[142:143], v[142:143], v[216:217]
	v_pk_mul_f32 v[144:145], v[144:145], v[204:205] op_sel:[0,1] op_sel_hi:[1,1]
	v_pk_mul_f32 v[146:147], v[146:147], v[204:205] op_sel:[0,1] op_sel_hi:[1,1]
	v_pk_mul_f32 v[136:137], v[136:137], v[204:205] op_sel:[0,1] op_sel_hi:[1,1]
	v_pk_mul_f32 v[138:139], v[138:139], v[204:205] op_sel:[0,1] op_sel_hi:[1,1]
	v_exp_f32_e32 v144, v144
	v_exp_f32_e32 v145, v145
	v_exp_f32_e32 v146, v146
	v_exp_f32_e32 v147, v147
	v_exp_f32_e32 v136, v136
	v_exp_f32_e32 v137, v137
	v_exp_f32_e32 v138, v138
	v_exp_f32_e32 v139, v139
	v_pk_add_f32 v[210:211], v[144:145], 1.0 op_sel_hi:[1,0] neg_lo:[1,0] neg_hi:[1,0]
	v_pk_add_f32 v[144:145], v[144:145], 1.0 op_sel_hi:[1,0]
	v_pk_add_f32 v[212:213], v[146:147], 1.0 op_sel_hi:[1,0] neg_lo:[1,0] neg_hi:[1,0]
	v_pk_add_f32 v[146:147], v[146:147], 1.0 op_sel_hi:[1,0]
	v_pk_add_f32 v[214:215], v[136:137], 1.0 op_sel_hi:[1,0] neg_lo:[1,0] neg_hi:[1,0]
	v_pk_add_f32 v[136:137], v[136:137], 1.0 op_sel_hi:[1,0]
	v_pk_add_f32 v[216:217], v[138:139], 1.0 op_sel_hi:[1,0] neg_lo:[1,0] neg_hi:[1,0]
	v_pk_add_f32 v[138:139], v[138:139], 1.0 op_sel_hi:[1,0]
	v_pk_mul_f32 v[144:145], v[210:211], v[144:145]
	v_pk_mul_f32 v[146:147], v[212:213], v[146:147]
	v_pk_mul_f32 v[136:137], v[214:215], v[136:137]
	v_pk_mul_f32 v[138:139], v[216:217], v[138:139]
	v_max_f32_e32 v144, 0, v144
	v_max_f32_e32 v145, 0, v145
	v_max_f32_e32 v146, 0, v146
	v_max_f32_e32 v147, 0, v147
	v_max_f32_e32 v136, 0, v136
	v_max_f32_e32 v137, 0, v137
	v_max_f32_e32 v138, 0, v138
	v_max_f32_e32 v139, 0, v139
	v_sqrt_f32_e32 v144, v144
	v_sqrt_f32_e32 v145, v145
	v_sqrt_f32_e32 v146, v146
	v_sqrt_f32_e32 v147, v147
	v_sqrt_f32_e32 v136, v136
	v_sqrt_f32_e32 v137, v137
	v_sqrt_f32_e32 v138, v138
	v_sqrt_f32_e32 v139, v139
	s_waitcnt lgkmcnt(0)
	v_lshlrev_b32_e32 v226, 16, v226
	v_lshlrev_b32_e32 v227, 16, v227
	v_lshlrev_b32_e32 v228, 16, v228
	v_lshlrev_b32_e32 v229, 16, v229
	v_lshlrev_b32_e32 v230, 16, v230
	v_lshlrev_b32_e32 v231, 16, v231
	v_lshlrev_b32_e32 v232, 16, v232
	v_lshlrev_b32_e32 v233, 16, v233
	v_pk_mul_f32 v[148:149], v[148:149], v[226:227]
	v_pk_mul_f32 v[150:151], v[150:151], v[228:229]
	v_pk_mul_f32 v[140:141], v[140:141], v[230:231]
	v_pk_mul_f32 v[142:143], v[142:143], v[232:233]
	v_pk_mul_f32 v[148:149], v[148:149], v[144:145]
	v_pk_mul_f32 v[150:151], v[150:151], v[146:147]
	v_pk_mul_f32 v[140:141], v[140:141], v[136:137]
	v_pk_mul_f32 v[142:143], v[142:143], v[138:139]
	v_cvt_pk_bf16_f32 v210, v210, v211
	v_cvt_pk_bf16_f32 v148, v148, v149
	v_cvt_pk_bf16_f32 v212, v212, v213
	v_cvt_pk_bf16_f32 v150, v150, v151
	v_cvt_pk_bf16_f32 v214, v214, v215
	v_cvt_pk_bf16_f32 v140, v140, v141
	v_cvt_pk_bf16_f32 v216, v216, v217
	v_cvt_pk_bf16_f32 v142, v142, v143
	ds_write_b16 v198, v210
	ds_write_b16_d16_hi v198, v210 offset:400
	ds_write_b16 v199, v148
	ds_write_b16_d16_hi v199, v148 offset:400
	ds_write_b16 v198, v212 offset:800
	ds_write_b16_d16_hi v198, v212 offset:1200
	ds_write_b16 v199, v150 offset:800
	ds_write_b16_d16_hi v199, v150 offset:1200
	ds_write_b16 v198, v214 offset:6400
	ds_write_b16_d16_hi v198, v214 offset:6800
	ds_write_b16 v199, v140 offset:6400
	ds_write_b16_d16_hi v199, v140 offset:6800
	ds_write_b16 v198, v216 offset:7200
	ds_write_b16_d16_hi v198, v216 offset:7600
	ds_write_b16 v199, v142 offset:7200
	ds_write_b16_d16_hi v199, v142 offset:7600
	s_branch .LBB0_847
